# static priority: one s_setprio 1 for waves 4-7 at the start of each attention unit (reset at unit end), the guide's static raise for the younger wave half in a 2-waves-per-SIMD MFMA+VALU loop
# speedup vs baseline: 1.0116x; 1.0116x over previous
.LBB0_1335:
	v_mov_b32_e32 v36, v204
	s_nop 0
	v_readfirstlane_b32 s28, v36
	s_ashr_i32 s55, s28, 6
	s_cmp_ge_i32 s55, 4
	s_cbranch_scc0 .Lattn_prio_done
	s_setprio 1
.Lattn_prio_done:
	s_lshl_b32 s44, s55, 5
	s_ashr_i32 s45, s44, 31
	v_and_b32_e32 v224, 63, v36
	s_lshl_b64 s[8:9], s[44:45], 10
	s_add_u32 s8, s38, s8
	v_lshlrev_b32_e32 v0, 10, v224
	s_addc_u32 s9, s39, s9
	v_lshl_add_u64 v[2:3], s[46:47], 0, v[0:1]
	s_lshl_b32 s10, s55, 3
	s_lshl_b32 s5, s55, 4
	v_bfe_u32 v0, v36, 2, 4
	s_ashr_i32 s11, s10, 31
	v_and_or_b32 v0, s5, 48, v0
	s_ashr_i32 s5, s28, 3
	v_lshl_add_u64 v[176:177], s[10:11], 1, v[2:3]
	s_and_b32 s10, s5, 0xffffffe0
	s_ashr_i32 s11, s10, 31
	s_lshl_b32 s38, s55, 10
	v_lshlrev_b32_e32 v0, 10, v0
	v_lshlrev_b32_e32 v225, 3, v36
	s_cmp_lg_u32 0, -1
	v_lshl_add_u64 v[2:3], s[48:49], 0, v[0:1]
	v_and_b32_e32 v228, 24, v225
	s_cselect_b32 s5, 0, 0
	v_bfe_u32 v227, v36, 5, 1
	v_lshl_add_u64 v[2:3], s[10:11], 1, v[2:3]
	v_lshlrev_b32_e32 v0, 1, v228
	s_add_i32 s5, s38, s5
	s_mov_b32 s10, m0
	s_mov_b32 m0, s5
	s_nop 0
	global_load_lds_dwordx4 v[176:177], off
	s_mov_b32 m0, s10
	v_and_b32_e32 v226, 31, v36
	v_lshl_add_u64 v[34:35], v[2:3], 0, v[0:1]
	s_add_i32 s56, s5, 0x6000
	s_mov_b32 s10, m0
	s_mov_b32 m0, s56
	s_nop 0
	global_load_lds_dwordx4 v[34:35], off
	s_mov_b32 m0, s10
	v_lshl_add_u64 v[2:3], v[176:177], 0, s[16:17]
	v_lshlrev_b32_e32 v5, 4, v227
	s_add_i32 s10, s5, 0x2000
	s_mov_b32 s11, m0
	s_mov_b32 m0, s10
	s_nop 0
	global_load_lds_dwordx4 v[2:3], off
	s_mov_b32 m0, s11
	v_lshl_or_b32 v2, v226, 10, v5
	global_load_dwordx4 v[124:127], v2, s[8:9]
	global_load_dwordx4 v[120:123], v2, s[8:9] offset:32
	global_load_dwordx4 v[116:119], v2, s[8:9] offset:64
	global_load_dwordx4 v[112:115], v2, s[8:9] offset:96
	v_lshlrev_b32_e32 v0, 10, v227
	v_lshlrev_b32_e32 v4, 4, v226
	v_add3_u32 v235, 0, v0, v4
	v_lshl_add_u64 v[2:3], v[176:177], 0, s[30:31]
	s_add_i32 s8, s5, 0x4000
	s_mov_b32 s9, m0
	s_mov_b32 m0, s8
	s_nop 0
	global_load_lds_dwordx4 v[2:3], off
	s_mov_b32 m0, s9
	v_add_u32_e32 v0, 0, v5
	s_waitcnt vmcnt(3) lgkmcnt(0)
	s_barrier
	v_add_u32_e32 v0, 0x15000, v0
	ds_read_b128 v[2:5], v0
	ds_read_b128 v[6:9], v0 offset:32
	ds_read_b128 v[10:13], v0 offset:128
	v_lshlrev_b32_e32 v229, 2, v227
	v_or_b32_e32 v234, s44, v226
	s_waitcnt lgkmcnt(2)
	v_xor_b32_e32 v5, 0x80000000, v5
	v_xor_b32_e32 v4, 0x80000000, v4
	s_waitcnt lgkmcnt(0)
	v_xor_b32_e32 v21, 0x80000000, v13
	v_xor_b32_e32 v20, 0x80000000, v12
	v_xor_b32_e32 v19, 0x80000000, v11
	v_xor_b32_e32 v18, 0x80000000, v10
	ds_read_b128 v[10:13], v0 offset:160
	v_xor_b32_e32 v3, 0x80000000, v3
	v_xor_b32_e32 v2, 0x80000000, v2
	v_xor_b32_e32 v6, 0x80000000, v6
	v_xor_b32_e32 v7, 0x80000000, v7
	s_waitcnt lgkmcnt(0)
	v_xor_b32_e32 v22, 0x80000000, v10
	v_xor_b32_e32 v23, 0x80000000, v11
	v_xor_b32_e32 v24, 0x80000000, v12
	v_xor_b32_e32 v25, 0x80000000, v13
	ds_read_b128 v[10:13], v0 offset:64
	ds_read_b128 v[14:17], v0 offset:192
	v_xor_b32_e32 v8, 0x80000000, v8
	v_xor_b32_e32 v9, 0x80000000, v9
	s_cmp_gt_u32 s4, 4
	s_waitcnt lgkmcnt(1)
	v_xor_b32_e32 v10, 0x80000000, v10
	s_waitcnt lgkmcnt(0)
	v_xor_b32_e32 v26, 0x80000000, v14
	v_xor_b32_e32 v27, 0x80000000, v15
	v_xor_b32_e32 v28, 0x80000000, v16
	v_xor_b32_e32 v29, 0x80000000, v17
	ds_read_b128 v[14:17], v0 offset:96
	ds_read_b128 v[30:33], v0 offset:224
	ds_read_b128 v[38:41], v235
	ds_read_b128 v[42:45], v235 offset:512
	v_xor_b32_e32 v11, 0x80000000, v11
	v_xor_b32_e32 v12, 0x80000000, v12
	v_xor_b32_e32 v13, 0x80000000, v13
	s_waitcnt lgkmcnt(3)
	v_xor_b32_e32 v14, 0x80000000, v14
	v_xor_b32_e32 v15, 0x80000000, v15
	v_xor_b32_e32 v16, 0x80000000, v16
	v_xor_b32_e32 v17, 0x80000000, v17
	s_waitcnt lgkmcnt(2)
	v_xor_b32_e32 v30, 0x80000000, v30
	v_xor_b32_e32 v31, 0x80000000, v31
	v_xor_b32_e32 v32, 0x80000000, v32
	v_xor_b32_e32 v33, 0x80000000, v33
	s_waitcnt vmcnt(3) lgkmcnt(1)
	v_mfma_f32_32x32x16_bf16 v[2:17], v[38:41], v[124:127], v[2:17]
	s_waitcnt lgkmcnt(0)
	v_mfma_f32_32x32x16_bf16 v[18:33], v[42:45], v[124:127], v[18:33]
	ds_read_b128 v[38:41], v235 offset:2048
	ds_read_b128 v[42:45], v235 offset:2560
	s_waitcnt vmcnt(2) lgkmcnt(1)
	v_mfma_f32_32x32x16_bf16 v[2:17], v[38:41], v[120:123], v[2:17]
	s_waitcnt lgkmcnt(0)
	v_mfma_f32_32x32x16_bf16 v[18:33], v[42:45], v[120:123], v[18:33]
	ds_read_b128 v[38:41], v235 offset:4096
	ds_read_b128 v[42:45], v235 offset:4608
	s_waitcnt vmcnt(1) lgkmcnt(1)
	v_mfma_f32_32x32x16_bf16 v[2:17], v[38:41], v[116:119], v[2:17]
	s_waitcnt lgkmcnt(0)
	v_mfma_f32_32x32x16_bf16 v[18:33], v[42:45], v[116:119], v[18:33]
	ds_read_b128 v[38:41], v235 offset:6144
	ds_read_b128 v[42:45], v235 offset:6656
	s_waitcnt vmcnt(0) lgkmcnt(1)
	v_mfma_f32_32x32x16_bf16 v[2:17], v[38:41], v[112:115], v[2:17]
	s_waitcnt lgkmcnt(0)
	v_mfma_f32_32x32x16_bf16 v[18:33], v[42:45], v[112:115], v[18:33]
	s_nop 15
	s_nop 7
	s_cbranch_scc1 .LBB0_1337
	v_or_b32_e32 v0, 32, v229
	v_cmp_le_i32_e32 vcc, v0, v234
	v_or_b32_e32 v0, 33, v229
	s_nop 7
	v_cndmask_b32_e32 v18, v223, v18, vcc
	v_cmp_lt_i32_e32 vcc, v229, v234
	s_nop 1
	v_cndmask_b32_e32 v3, v223, v3, vcc
	v_cmp_le_i32_e32 vcc, v229, v234
	s_nop 1
	v_cndmask_b32_e32 v2, v223, v2, vcc
	v_cmp_le_i32_e32 vcc, v0, v234
	v_or_b32_e32 v0, 2, v229
	s_nop 0
	v_cndmask_b32_e32 v19, v223, v19, vcc
	v_cmp_le_i32_e32 vcc, v0, v234
	v_or_b32_e32 v0, 34, v229
	s_nop 0
	v_cndmask_b32_e32 v4, v223, v4, vcc
	v_cmp_le_i32_e32 vcc, v0, v234
	v_or_b32_e32 v0, 3, v229
	s_nop 0
	v_cndmask_b32_e32 v20, v223, v20, vcc
	v_cmp_le_i32_e32 vcc, v0, v234
	v_or_b32_e32 v0, 35, v229
	s_nop 0
	v_cndmask_b32_e32 v5, v223, v5, vcc
	v_cmp_le_i32_e32 vcc, v0, v234
	v_or_b32_e32 v0, 8, v229
	s_nop 0
	v_cndmask_b32_e32 v21, v223, v21, vcc
	v_cmp_le_i32_e32 vcc, v0, v234
	v_or_b32_e32 v0, 40, v229
	s_nop 0
	v_cndmask_b32_e32 v6, v223, v6, vcc
	v_cmp_le_i32_e32 vcc, v0, v234
	v_or_b32_e32 v0, 9, v229
	s_nop 0
	v_cndmask_b32_e32 v22, v223, v22, vcc
	v_cmp_le_i32_e32 vcc, v0, v234
	v_or_b32_e32 v0, 41, v229
	s_nop 0
	v_cndmask_b32_e32 v7, v223, v7, vcc
	v_cmp_le_i32_e32 vcc, v0, v234
	v_or_b32_e32 v0, 10, v229
	s_nop 0
	v_cndmask_b32_e32 v23, v223, v23, vcc
	v_cmp_le_i32_e32 vcc, v0, v234
	v_or_b32_e32 v0, 42, v229
	s_nop 0
	v_cndmask_b32_e32 v8, v223, v8, vcc
	v_cmp_le_i32_e32 vcc, v0, v234
	v_or_b32_e32 v0, 11, v229
	s_nop 0
	v_cndmask_b32_e32 v24, v223, v24, vcc
	v_cmp_le_i32_e32 vcc, v0, v234
	v_or_b32_e32 v0, 43, v229
	s_nop 0
	v_cndmask_b32_e32 v9, v223, v9, vcc
	v_cmp_le_i32_e32 vcc, v0, v234
	v_or_b32_e32 v0, 16, v229
	s_nop 0
	v_cndmask_b32_e32 v25, v223, v25, vcc
	v_cmp_le_i32_e32 vcc, v0, v234
	v_or_b32_e32 v0, 48, v229
	s_nop 0
	v_cndmask_b32_e32 v10, v223, v10, vcc
	v_cmp_le_i32_e32 vcc, v0, v234
	v_or_b32_e32 v0, 17, v229
	s_nop 0
	v_cndmask_b32_e32 v26, v223, v26, vcc
	v_cmp_le_i32_e32 vcc, v0, v234
	v_or_b32_e32 v0, 49, v229
	s_nop 0
	v_cndmask_b32_e32 v11, v223, v11, vcc
	v_cmp_le_i32_e32 vcc, v0, v234
	v_or_b32_e32 v0, 18, v229
	s_nop 0
	v_cndmask_b32_e32 v27, v223, v27, vcc
	v_cmp_le_i32_e32 vcc, v0, v234
	v_or_b32_e32 v0, 50, v229
	s_nop 0
	v_cndmask_b32_e32 v12, v223, v12, vcc
	v_cmp_le_i32_e32 vcc, v0, v234
	v_or_b32_e32 v0, 19, v229
	s_nop 0
	v_cndmask_b32_e32 v28, v223, v28, vcc
	v_cmp_le_i32_e32 vcc, v0, v234
	v_or_b32_e32 v0, 51, v229
	s_nop 0
	v_cndmask_b32_e32 v13, v223, v13, vcc
	v_cmp_le_i32_e32 vcc, v0, v234
	v_or_b32_e32 v0, 24, v229
	s_nop 0
	v_cndmask_b32_e32 v29, v223, v29, vcc
	v_cmp_le_i32_e32 vcc, v0, v234
	v_or_b32_e32 v0, 56, v229
	s_nop 0
	v_cndmask_b32_e32 v14, v223, v14, vcc
	v_cmp_le_i32_e32 vcc, v0, v234
	v_or_b32_e32 v0, 25, v229
	s_nop 0
	v_cndmask_b32_e32 v30, v223, v30, vcc
	v_cmp_le_i32_e32 vcc, v0, v234
	v_or_b32_e32 v0, 57, v229
	s_nop 0
	v_cndmask_b32_e32 v15, v223, v15, vcc
	v_cmp_le_i32_e32 vcc, v0, v234
	v_or_b32_e32 v0, 26, v229
	s_nop 0
	v_cndmask_b32_e32 v31, v223, v31, vcc
	v_cmp_le_i32_e32 vcc, v0, v234
	v_or_b32_e32 v0, 58, v229
	s_nop 0
	v_cndmask_b32_e32 v16, v223, v16, vcc
	v_cmp_le_i32_e32 vcc, v0, v234
	v_or_b32_e32 v0, 27, v229
	s_nop 0
	v_cndmask_b32_e32 v32, v223, v32, vcc
	v_cmp_le_i32_e32 vcc, v0, v234
	v_or_b32_e32 v0, 59, v229
	s_nop 0
	v_cndmask_b32_e32 v17, v223, v17, vcc
	v_cmp_le_i32_e32 vcc, v0, v234
	s_nop 1
	v_cndmask_b32_e32 v33, v223, v33, vcc

.LBB0_1369:
	s_setprio 0
	s_waitcnt lgkmcnt(0)
	s_barrier
